# E19: ret_kv MFMA operand swap -> 16 dwordx4 stores instead of 64 dword stores, counted vmcnt ladder in ret_kv loop (on E10)
# baseline (speedup 1.0000x reference)
.Lmy_kv_first:
	s_add_i32 s5, s5, s4
	s_cmpk_gt_i32 s5, 0x1ff
	s_cselect_b64 s[16:17], -1, 0
	s_and_b64 vcc, exec, s[16:17]
	s_barrier
	s_waitcnt vmcnt(11)
	ds_write_b128 v86, v[4:7]
	s_waitcnt vmcnt(10)
	ds_write_b128 v87, v[8:11]
	s_waitcnt vmcnt(9)
	ds_write_b128 v88, v[12:15]
	s_waitcnt vmcnt(8)
	ds_write_b128 v89, v[16:19]
	s_waitcnt vmcnt(7)
	ds_write_b128 v90, v[20:23] offset:36864
	s_waitcnt vmcnt(6)
	ds_write_b128 v91, v[24:27] offset:36864
	s_waitcnt vmcnt(5)
	ds_write_b128 v92, v[28:31] offset:36864
	s_waitcnt vmcnt(4)
	ds_write_b128 v93, v[32:35] offset:36864
	s_waitcnt vmcnt(3)
	ds_write_b128 v94, v[36:39] offset:36864
	s_waitcnt vmcnt(2)
	ds_write_b128 v95, v[40:43] offset:36864
	s_waitcnt vmcnt(1)
	ds_write_b128 v96, v[44:47] offset:36864
	s_waitcnt vmcnt(0)
	ds_write_b128 v97, v[48:51] offset:36864
	s_branch .Lmy_kv_ladder_done
.LBB0_1360:
	s_waitcnt lgkmcnt(0)
	s_barrier
	v_add_u32_e32 v176, v84, v2
	ds_read_b64_tr_b16 v[108:109], v176 offset:45568
	ds_read_b64_tr_b16 v[106:107], v176 offset:36864
	ds_read_b64_tr_b16 v[110:111], v176 offset:36896
	ds_read_b64_tr_b16 v[112:113], v176 offset:45600
	ds_read_b64_tr_b16 v[116:117], v99
	ds_read_b64_tr_b16 v[120:121], v99 offset:32
	ds_read_b64_tr_b16 v[114:115], v98
	ds_read_b64_tr_b16 v[118:119], v98 offset:32
	ds_read_b64_tr_b16 v[122:123], v98 offset:64
	ds_read_b64_tr_b16 v[124:125], v99 offset:64
	ds_read_b64_tr_b16 v[126:127], v98 offset:96
	ds_read_b64_tr_b16 v[128:129], v99 offset:96
	ds_read_b64_tr_b16 v[130:131], v98 offset:128
	ds_read_b64_tr_b16 v[132:133], v99 offset:128
	ds_read_b64_tr_b16 v[134:135], v98 offset:160
	ds_read_b64_tr_b16 v[136:137], v99 offset:160
	ds_read_b64_tr_b16 v[138:139], v98 offset:192
	ds_read_b64_tr_b16 v[140:141], v99 offset:192
	ds_read_b64_tr_b16 v[142:143], v98 offset:224
	ds_read_b64_tr_b16 v[144:145], v99 offset:224
	s_waitcnt lgkmcnt(13)
	v_mfma_f32_16x16x32_bf16 v[146:149], v[114:117], v[106:109], 0
	v_add_u32_e32 v225, v85, v2
	s_add_i32 s0, s0, s1
	s_andn2_b64 vcc, exec, s[16:17]
	v_mfma_f32_16x16x32_bf16 v[114:117], v[114:117], v[110:113], 0
	s_waitcnt lgkmcnt(12)
	v_mfma_f32_16x16x32_bf16 v[150:153], v[118:121], v[106:109], 0
	v_mfma_f32_16x16x32_bf16 v[118:121], v[118:121], v[110:113], 0
	s_waitcnt lgkmcnt(10)
	v_mfma_f32_16x16x32_bf16 v[154:157], v[122:125], v[106:109], 0
	v_mfma_f32_16x16x32_bf16 v[122:125], v[122:125], v[110:113], 0
	s_waitcnt lgkmcnt(8)
	v_mfma_f32_16x16x32_bf16 v[158:161], v[126:129], v[106:109], 0
	v_mfma_f32_16x16x32_bf16 v[126:129], v[126:129], v[110:113], 0
	s_waitcnt lgkmcnt(6)
	v_mfma_f32_16x16x32_bf16 v[162:165], v[130:133], v[106:109], 0
	v_mfma_f32_16x16x32_bf16 v[130:133], v[130:133], v[110:113], 0
	s_waitcnt lgkmcnt(4)
	v_mfma_f32_16x16x32_bf16 v[166:169], v[134:137], v[106:109], 0
	v_mfma_f32_16x16x32_bf16 v[134:137], v[134:137], v[110:113], 0
	s_waitcnt lgkmcnt(2)
	v_mfma_f32_16x16x32_bf16 v[170:173], v[138:141], v[106:109], 0
	v_mfma_f32_16x16x32_bf16 v[138:141], v[138:141], v[110:113], 0
	s_waitcnt lgkmcnt(0)
	v_mfma_f32_16x16x32_bf16 v[106:109], v[142:145], v[106:109], 0
	v_mfma_f32_16x16x32_bf16 v[110:113], v[142:145], v[110:113], 0
	ds_read_b64_tr_b16 v[142:143], v176 offset:54272
	ds_read_b64_tr_b16 v[144:145], v176 offset:62976
	ds_read_b64_tr_b16 v[174:175], v176 offset:54304
	ds_read_b64_tr_b16 v[176:177], v176 offset:63008
	ds_read_b64_tr_b16 v[180:181], v101
	ds_read_b64_tr_b16 v[184:185], v101 offset:32
	ds_read_b64_tr_b16 v[178:179], v100
	ds_read_b64_tr_b16 v[182:183], v100 offset:32
	ds_read_b64_tr_b16 v[186:187], v100 offset:64
	ds_read_b64_tr_b16 v[188:189], v101 offset:64
	ds_read_b64_tr_b16 v[190:191], v100 offset:96
	ds_read_b64_tr_b16 v[192:193], v101 offset:96
	ds_read_b64_tr_b16 v[194:195], v100 offset:128
	ds_read_b64_tr_b16 v[196:197], v101 offset:128
	ds_read_b64_tr_b16 v[198:199], v100 offset:160
	ds_read_b64_tr_b16 v[200:201], v101 offset:160
	ds_read_b64_tr_b16 v[202:203], v100 offset:192
	ds_read_b64_tr_b16 v[204:205], v101 offset:192
	ds_read_b64_tr_b16 v[206:207], v100 offset:224
	ds_read_b64_tr_b16 v[208:209], v101 offset:224
	s_waitcnt lgkmcnt(13)
	v_mfma_f32_16x16x32_bf16 v[146:149], v[178:181], v[142:145], v[146:149]
	v_mfma_f32_16x16x32_bf16 v[114:117], v[178:181], v[174:177], v[114:117]
	s_waitcnt lgkmcnt(12)
	v_mfma_f32_16x16x32_bf16 v[150:153], v[182:185], v[142:145], v[150:153]
	v_mfma_f32_16x16x32_bf16 v[118:121], v[182:185], v[174:177], v[118:121]
	s_waitcnt lgkmcnt(10)
	v_mfma_f32_16x16x32_bf16 v[154:157], v[186:189], v[142:145], v[154:157]
	v_mfma_f32_16x16x32_bf16 v[122:125], v[186:189], v[174:177], v[122:125]
	s_waitcnt lgkmcnt(8)
	v_mfma_f32_16x16x32_bf16 v[158:161], v[190:193], v[142:145], v[158:161]
	v_mfma_f32_16x16x32_bf16 v[126:129], v[190:193], v[174:177], v[126:129]
	s_waitcnt lgkmcnt(6)
	v_mfma_f32_16x16x32_bf16 v[162:165], v[194:197], v[142:145], v[162:165]
	v_mfma_f32_16x16x32_bf16 v[130:133], v[194:197], v[174:177], v[130:133]
	s_waitcnt lgkmcnt(4)
	v_mfma_f32_16x16x32_bf16 v[166:169], v[198:201], v[142:145], v[166:169]
	v_mfma_f32_16x16x32_bf16 v[134:137], v[198:201], v[174:177], v[134:137]
	s_waitcnt lgkmcnt(2)
	v_mfma_f32_16x16x32_bf16 v[170:173], v[202:205], v[142:145], v[170:173]
	v_mfma_f32_16x16x32_bf16 v[138:141], v[202:205], v[174:177], v[138:141]
	s_waitcnt lgkmcnt(0)
	v_mfma_f32_16x16x32_bf16 v[106:109], v[206:209], v[142:145], v[106:109]
	v_mfma_f32_16x16x32_bf16 v[110:113], v[206:209], v[174:177], v[110:113]
	ds_read_b64_tr_b16 v[144:145], v225 offset:45568
	ds_read_b64_tr_b16 v[142:143], v225 offset:36864
	ds_read_b64_tr_b16 v[174:175], v225 offset:36896
	ds_read_b64_tr_b16 v[176:177], v225 offset:45600
	ds_read_b64_tr_b16 v[180:181], v103
	ds_read_b64_tr_b16 v[184:185], v103 offset:32
	ds_read_b64_tr_b16 v[178:179], v102
	ds_read_b64_tr_b16 v[182:183], v102 offset:32
	ds_read_b64_tr_b16 v[186:187], v102 offset:64
	ds_read_b64_tr_b16 v[188:189], v103 offset:64
	ds_read_b64_tr_b16 v[190:191], v102 offset:96
	ds_read_b64_tr_b16 v[192:193], v103 offset:96
	ds_read_b64_tr_b16 v[194:195], v102 offset:128
	ds_read_b64_tr_b16 v[196:197], v103 offset:128
	ds_read_b64_tr_b16 v[198:199], v102 offset:160
	ds_read_b64_tr_b16 v[200:201], v103 offset:160
	ds_read_b64_tr_b16 v[202:203], v102 offset:192
	ds_read_b64_tr_b16 v[204:205], v103 offset:192
	ds_read_b64_tr_b16 v[206:207], v102 offset:224
	ds_read_b64_tr_b16 v[208:209], v103 offset:224
	s_waitcnt lgkmcnt(13)
	v_mfma_f32_16x16x32_bf16 v[146:149], v[178:181], v[142:145], v[146:149]
	v_mfma_f32_16x16x32_bf16 v[114:117], v[178:181], v[174:177], v[114:117]
	s_waitcnt lgkmcnt(12)
	v_mfma_f32_16x16x32_bf16 v[150:153], v[182:185], v[142:145], v[150:153]
	v_mfma_f32_16x16x32_bf16 v[118:121], v[182:185], v[174:177], v[118:121]
	s_waitcnt lgkmcnt(10)
	v_mfma_f32_16x16x32_bf16 v[154:157], v[186:189], v[142:145], v[154:157]
	v_mfma_f32_16x16x32_bf16 v[122:125], v[186:189], v[174:177], v[122:125]
	s_waitcnt lgkmcnt(8)
	v_mfma_f32_16x16x32_bf16 v[158:161], v[190:193], v[142:145], v[158:161]
	v_mfma_f32_16x16x32_bf16 v[126:129], v[190:193], v[174:177], v[126:129]
	s_waitcnt lgkmcnt(6)
	v_mfma_f32_16x16x32_bf16 v[162:165], v[194:197], v[142:145], v[162:165]
	v_mfma_f32_16x16x32_bf16 v[130:133], v[194:197], v[174:177], v[130:133]
	s_waitcnt lgkmcnt(4)
	v_mfma_f32_16x16x32_bf16 v[166:169], v[198:201], v[142:145], v[166:169]
	v_mfma_f32_16x16x32_bf16 v[134:137], v[198:201], v[174:177], v[134:137]
	s_waitcnt lgkmcnt(2)
	v_mfma_f32_16x16x32_bf16 v[170:173], v[202:205], v[142:145], v[170:173]
	v_mfma_f32_16x16x32_bf16 v[138:141], v[202:205], v[174:177], v[138:141]
	s_waitcnt lgkmcnt(0)
	v_mfma_f32_16x16x32_bf16 v[106:109], v[206:209], v[142:145], v[106:109]
	v_mfma_f32_16x16x32_bf16 v[110:113], v[206:209], v[174:177], v[110:113]
	ds_read_b64_tr_b16 v[142:143], v225 offset:54272
	ds_read_b64_tr_b16 v[144:145], v225 offset:62976
	ds_read_b64_tr_b16 v[174:175], v225 offset:54304
	ds_read_b64_tr_b16 v[176:177], v225 offset:63008
	ds_read_b64_tr_b16 v[180:181], v105
	ds_read_b64_tr_b16 v[184:185], v105 offset:32
	ds_read_b64_tr_b16 v[178:179], v104
	ds_read_b64_tr_b16 v[182:183], v104 offset:32
	ds_read_b64_tr_b16 v[186:187], v104 offset:64
	ds_read_b64_tr_b16 v[188:189], v105 offset:64
	ds_read_b64_tr_b16 v[190:191], v104 offset:96
	ds_read_b64_tr_b16 v[192:193], v105 offset:96
	ds_read_b64_tr_b16 v[194:195], v104 offset:128
	ds_read_b64_tr_b16 v[196:197], v105 offset:128
	ds_read_b64_tr_b16 v[198:199], v104 offset:160
	ds_read_b64_tr_b16 v[200:201], v105 offset:160
	ds_read_b64_tr_b16 v[202:203], v104 offset:192
	ds_read_b64_tr_b16 v[204:205], v105 offset:192
	ds_read_b64_tr_b16 v[206:207], v104 offset:224
	ds_read_b64_tr_b16 v[208:209], v105 offset:224
	s_waitcnt lgkmcnt(13)
	v_mfma_f32_16x16x32_bf16 v[146:149], v[178:181], v[142:145], v[146:149]
	v_mfma_f32_16x16x32_bf16 v[114:117], v[178:181], v[174:177], v[114:117]
	s_waitcnt lgkmcnt(12)
	v_mfma_f32_16x16x32_bf16 v[150:153], v[182:185], v[142:145], v[150:153]
	s_waitcnt lgkmcnt(10)
	v_mfma_f32_16x16x32_bf16 v[154:157], v[186:189], v[142:145], v[154:157]
	s_waitcnt lgkmcnt(8)
	v_mfma_f32_16x16x32_bf16 v[158:161], v[190:193], v[142:145], v[158:161]
	s_waitcnt lgkmcnt(6)
	v_mfma_f32_16x16x32_bf16 v[162:165], v[194:197], v[142:145], v[162:165]
	s_waitcnt lgkmcnt(4)
	v_mfma_f32_16x16x32_bf16 v[166:169], v[198:201], v[142:145], v[166:169]
	s_waitcnt lgkmcnt(2)
	v_mfma_f32_16x16x32_bf16 v[170:173], v[202:205], v[142:145], v[170:173]
	s_waitcnt lgkmcnt(0)
	v_mfma_f32_16x16x32_bf16 v[106:109], v[206:209], v[142:145], v[106:109]
	v_lshl_add_u64 v[142:143], v[80:81], 0, v[82:83]
	v_mbcnt_lo_u32_b32 v144, -1, 0
	v_mbcnt_hi_u32_b32 v144, -1, v144
	v_and_b32_e32 v145, 15, v144
	v_lshrrev_b32_e32 v144, 4, v144
	v_mul_u32_u24_e32 v145, 0x1fc, v145
	v_mul_u32_u24_e32 v144, 0x7f0, v144
	v_sub_u32_e32 v144, v145, v144
	v_add_u32_e32 v144, 0xfffffc00, v144
	v_ashrrev_i32_e32 v145, 31, v144
	v_lshl_add_u64 v[142:143], v[142:143], 0, v[144:145]
	global_store_dwordx4 v[142:143], v[146:149], off
	global_store_dwordx4 v[142:143], v[150:153], off offset:64
	global_store_dwordx4 v[142:143], v[154:157], off offset:128
	global_store_dwordx4 v[142:143], v[158:161], off offset:192
	global_store_dwordx4 v[142:143], v[162:165], off offset:256
	global_store_dwordx4 v[142:143], v[166:169], off offset:320
	global_store_dwordx4 v[142:143], v[170:173], off offset:384
	global_store_dwordx4 v[142:143], v[106:109], off offset:448
	s_nop 1
	v_lshl_add_u64 v[106:107], v[80:81], 0, v[78:79]
	v_lshl_add_u64 v[106:107], v[106:107], 0, v[144:145]
	v_lshl_add_u64 v[80:81], v[80:81], 0, s[6:7]
	v_mfma_f32_16x16x32_bf16 v[118:121], v[182:185], v[174:177], v[118:121]
	v_mfma_f32_16x16x32_bf16 v[122:125], v[186:189], v[174:177], v[122:125]
	v_mfma_f32_16x16x32_bf16 v[126:129], v[190:193], v[174:177], v[126:129]
	v_mfma_f32_16x16x32_bf16 v[130:133], v[194:197], v[174:177], v[130:133]
	v_mfma_f32_16x16x32_bf16 v[134:137], v[198:201], v[174:177], v[134:137]
	v_mfma_f32_16x16x32_bf16 v[138:141], v[202:205], v[174:177], v[138:141]
	v_mfma_f32_16x16x32_bf16 v[110:113], v[206:209], v[174:177], v[110:113]
	s_nop 3
	global_store_dwordx4 v[106:107], v[114:117], off
	global_store_dwordx4 v[106:107], v[118:121], off offset:64
	global_store_dwordx4 v[106:107], v[122:125], off offset:128
	global_store_dwordx4 v[106:107], v[126:129], off offset:192
	global_store_dwordx4 v[106:107], v[130:133], off offset:256
	global_store_dwordx4 v[106:107], v[134:137], off offset:320
	global_store_dwordx4 v[106:107], v[138:141], off offset:384
	global_store_dwordx4 v[106:107], v[110:113], off offset:448
	s_cbranch_vccz .LBB0_1363
.LBB0_1361:
	s_add_i32 s5, s5, s4
	s_cmpk_gt_i32 s5, 0x1ff
	s_cselect_b64 s[16:17], -1, 0
	s_and_b64 vcc, exec, s[16:17]
	s_barrier
	s_waitcnt vmcnt(27)
	ds_write_b128 v86, v[4:7]
	s_waitcnt vmcnt(26)
	ds_write_b128 v87, v[8:11]
	s_waitcnt vmcnt(25)
	ds_write_b128 v88, v[12:15]
	s_waitcnt vmcnt(24)
	ds_write_b128 v89, v[16:19]
	s_waitcnt vmcnt(23)
	ds_write_b128 v90, v[20:23] offset:36864
	s_waitcnt vmcnt(22)
	ds_write_b128 v91, v[24:27] offset:36864
	s_waitcnt vmcnt(21)
	ds_write_b128 v92, v[28:31] offset:36864
	s_waitcnt vmcnt(20)
	ds_write_b128 v93, v[32:35] offset:36864
	s_waitcnt vmcnt(19)
	ds_write_b128 v94, v[36:39] offset:36864
	s_waitcnt vmcnt(18)
	ds_write_b128 v95, v[40:43] offset:36864
	s_waitcnt vmcnt(17)
	ds_write_b128 v96, v[44:47] offset:36864
	s_waitcnt vmcnt(16)
	ds_write_b128 v97, v[48:51] offset:36864
.Lmy_kv_ladder_done:
	s_cbranch_vccnz .LBB0_1360
	s_ashr_i32 s18, s5, 8
	s_ashr_i32 s19, s18, 31
	s_bfe_u32 s24, s5, 0x20006
	s_lshl_b64 s[18:19], s[18:19], 13
	s_and_b32 s2, s0, 0x1f80
	s_or_b32 s18, s18, s2
	s_lshl_b32 s2, s24, 8
	v_lshl_add_u64 v[12:13], v[74:75], 0, s[2:3]
	v_lshl_add_u64 v[4:5], s[18:19], 0, v[0:1]
	v_lshl_add_u64 v[6:7], s[18:19], 0, v[52:53]
	v_lshl_add_u64 v[14:15], s[18:19], 0, v[54:55]
	v_lshl_add_u64 v[16:17], s[18:19], 0, v[56:57]
	s_lshl_b32 s2, s24, 9
	v_lshl_add_u64 v[20:21], s[18:19], 0, v[58:59]
	v_lshl_add_u64 v[22:23], s[18:19], 0, v[60:61]
	v_lshl_add_u64 v[28:29], s[18:19], 0, v[62:63]
	v_lshl_add_u64 v[30:31], s[18:19], 0, v[64:65]
	v_lshl_add_u64 v[36:37], s[18:19], 0, v[66:67]
	v_lshl_add_u64 v[38:39], s[18:19], 0, v[68:69]
	v_lshl_add_u64 v[46:47], s[18:19], 0, v[70:71]
	v_lshl_add_u64 v[48:49], s[18:19], 0, v[72:73]
	v_lshlrev_b64 v[4:5], 10, v[4:5]
	v_lshlrev_b64 v[6:7], 10, v[6:7]
	v_lshlrev_b64 v[14:15], 10, v[14:15]
	v_lshlrev_b64 v[16:17], 10, v[16:17]
	v_lshl_add_u64 v[44:45], v[76:77], 0, s[2:3]
	v_lshlrev_b64 v[20:21], 11, v[20:21]
	v_lshlrev_b64 v[22:23], 11, v[22:23]
	v_lshlrev_b64 v[28:29], 11, v[28:29]
	v_lshlrev_b64 v[30:31], 11, v[30:31]
	v_lshlrev_b64 v[36:37], 11, v[36:37]
	v_lshlrev_b64 v[38:39], 11, v[38:39]
	v_lshlrev_b64 v[46:47], 11, v[46:47]
	v_lshlrev_b64 v[48:49], 11, v[48:49]
	v_lshl_add_u64 v[4:5], v[12:13], 0, v[4:5]
	v_lshl_add_u64 v[8:9], v[12:13], 0, v[6:7]
	v_lshl_add_u64 v[14:15], v[12:13], 0, v[14:15]
	v_lshl_add_u64 v[16:17], v[12:13], 0, v[16:17]
	v_lshl_add_u64 v[20:21], v[44:45], 0, v[20:21]
	v_lshl_add_u64 v[24:25], v[44:45], 0, v[22:23]
	v_lshl_add_u64 v[28:29], v[44:45], 0, v[28:29]
	v_lshl_add_u64 v[32:33], v[44:45], 0, v[30:31]
	v_lshl_add_u64 v[36:37], v[44:45], 0, v[36:37]
	v_lshl_add_u64 v[40:41], v[44:45], 0, v[38:39]
	v_lshl_add_u64 v[46:47], v[44:45], 0, v[46:47]
	v_lshl_add_u64 v[48:49], v[44:45], 0, v[48:49]
	global_load_dwordx4 v[4:7], v[4:5], off
	s_nop 0
	global_load_dwordx4 v[8:11], v[8:9], off
	s_nop 0
	global_load_dwordx4 v[12:15], v[14:15], off
	s_nop 0
	global_load_dwordx4 v[16:19], v[16:17], off
	s_nop 0
	global_load_dwordx4 v[20:23], v[20:21], off
	s_nop 0
	global_load_dwordx4 v[24:27], v[24:25], off
	s_nop 0
	global_load_dwordx4 v[28:31], v[28:29], off
	s_nop 0
	global_load_dwordx4 v[32:35], v[32:33], off
	s_nop 0
	global_load_dwordx4 v[36:39], v[36:37], off
	s_nop 0
	global_load_dwordx4 v[40:43], v[40:41], off
	s_nop 0
	global_load_dwordx4 v[44:47], v[46:47], off
	s_nop 0
	global_load_dwordx4 v[48:51], v[48:49], off
	s_branch .LBB0_1360
